# compressed-attention head loop: q rows and gate of the next head loaded one head ahead
# speedup vs baseline: 1.0015x; 1.0015x over previous
.LBB0_2007:
	s_ashr_i32 s12, s33, 4
	s_ashr_i32 s13, s12, 31
	s_lshl_b64 s[0:1], s[12:13], 14
	v_lshl_add_u64 v[8:9], v[40:41], 0, s[0:1]
	v_lshl_add_u64 v[10:11], v[42:43], 0, s[0:1]
	v_mov_b32_e32 v53, v37
	v_mov_b32_e32 v55, v37
	v_mov_b32_e32 v57, v37
	v_mov_b32_e32 v59, v37
	s_waitcnt lgkmcnt(0)
	v_lshl_add_u64 v[0:1], v[8:9], 0, v[52:53]
	v_lshl_add_u64 v[4:5], v[10:11], 0, v[54:55]
	v_lshl_add_u64 v[8:9], v[8:9], 0, v[56:57]
	v_lshl_add_u64 v[12:13], v[10:11], 0, v[58:59]
	s_barrier
	global_load_dwordx4 v[0:3], v[0:1], off
	s_nop 0
	global_load_dwordx4 v[4:7], v[4:5], off
	s_nop 0
	global_load_dwordx4 v[8:11], v[8:9], off
	s_nop 0
	global_load_dwordx4 v[12:15], v[12:13], off
	s_lshl_b32 s13, s33, 3
	s_lshr_b32 s1, s95, 3
	s_lshl_b32 s90, s12, 7
	s_and_b32 s12, s13, 0x78
	v_readlane_b32 s18, v251, 7
	s_lshl_b32 s1, s1, 7
	s_add_i32 s12, s12, s18
	s_add_i32 s1, s7, s1
	s_add_i32 s14, s12, s90
	s_and_b32 s1, s1, 0x7f0
	s_lshl_b32 s13, s12, 4
	s_ashr_i32 s12, s14, 8
	v_or_b32_e32 v17, s1, v99
	s_and_b32 s1, s13, 0x7f0
	s_ashr_i32 s13, s12, 31
	s_and_b32 s15, s95, 0x78
	s_lshl_b64 s[24:25], s[12:13], 17
	v_add_u32_e32 v16, v140, v196
	v_or_b32_e32 v53, s1, v99
	s_add_u32 s16, s24, 0x13000000
	v_subrev_u32_e32 v18, 31, v53
	s_addc_u32 s17, s25, 0
	v_lshrrev_b32_e32 v18, 4, v18
	v_add_u32_e32 v18, 1, v18
	v_cmp_lt_u32_e32 vcc, 30, v53
	v_lshlrev_b32_e32 v36, 10, v17
	v_mov_b32_e32 v86, 0
	v_cndmask_b32_e32 v18, 0, v18, vcc
	s_lshl_b64 vcc, s[12:13], 21
	s_mov_b32 s0, 4
	v_cmp_lt_u32_e64 s[24:25], v194, v18
	v_cmp_lt_u32_e64 s[26:27], v101, v18
	v_cmp_lt_u32_e64 s[28:29], v102, v18
	v_cmp_lt_u32_e64 s[30:31], v103, v18
	v_cmp_lt_u32_e64 s[34:35], v104, v18
	v_cmp_lt_u32_e64 s[36:37], v105, v18
	v_cmp_lt_u32_e64 s[38:39], v106, v18
	v_cmp_lt_u32_e64 s[40:41], v107, v18
	v_cmp_lt_u32_e64 s[42:43], v108, v18
	v_cmp_lt_u32_e64 s[44:45], v109, v18
	v_cmp_lt_u32_e64 s[46:47], v110, v18
	v_cmp_lt_u32_e64 s[48:49], v111, v18
	v_cmp_lt_u32_e64 s[50:51], v112, v18
	v_cmp_lt_u32_e64 s[52:53], v113, v18
	v_cmp_lt_u32_e64 s[54:55], v114, v18
	v_cmp_lt_u32_e64 s[56:57], v115, v18
	v_cmp_lt_u32_e64 s[58:59], v116, v18
	v_cmp_lt_u32_e64 s[60:61], v117, v18
	v_cmp_lt_u32_e64 s[62:63], v118, v18
	v_cmp_lt_u32_e64 s[64:65], v119, v18
	v_cmp_lt_u32_e64 s[66:67], v120, v18
	v_cmp_lt_u32_e64 s[68:69], v121, v18
	v_cmp_lt_u32_e64 s[70:71], v122, v18
	v_cmp_lt_u32_e64 s[72:73], v123, v18
	v_cmp_lt_u32_e64 s[74:75], v124, v18
	v_cmp_lt_u32_e64 s[76:77], v125, v18
	v_cmp_lt_u32_e64 s[78:79], v126, v18
	v_cmp_lt_u32_e64 s[80:81], v127, v18
	v_cmp_lt_u32_e64 s[82:83], v128, v18
	v_cmp_lt_u32_e64 s[84:85], v129, v18
	v_cmp_lt_u32_e64 s[86:87], v130, v18
	v_cmp_lt_u32_e64 s[88:89], v131, v18
	v_mov_b32_e32 v93, s17
	v_mov_b32_e32 v95, vcc_hi
	v_mov_b32_e32 v87, v86
	v_mov_b32_e32 v84, v86
	v_mov_b32_e32 v85, v86
	s_waitcnt vmcnt(3)
	ds_write_b128 v16, v[0:3]
	s_waitcnt vmcnt(2)
	ds_write_b128 v148, v[4:7] offset:18432
	s_waitcnt vmcnt(1)
	ds_write_b128 v149, v[8:11]
	s_waitcnt vmcnt(0)
	ds_write_b128 v150, v[12:15] offset:18432
	v_lshl_or_b32 v0, v17, 6, s16
	s_add_i32 s16, s18, s90
	s_add_i32 s16, s16, s15
	s_bfe_u32 s15, s16, 0x10007
	s_mul_i32 s15, s15, 24
	s_lshl_b32 s13, s16, 2
	v_or_b32_e32 v92, s15, v0
	v_or_b32_e32 v0, vcc_lo, v154
	s_and_b32 s90, s13, 0x200
	v_or3_b32 v94, v0, v36, s90
	v_lshl_add_u64 v[0:1], v[50:51], 0, vcc
	v_lshl_add_u64 v[0:1], v[0:1], 0, v[36:37]
	v_lshl_add_u64 v[96:97], v[0:1], 0, s[90:91]
	v_mov_b32_e32 v90, v86
	v_mov_b32_e32 v91, v86
	v_mov_b32_e32 v88, v86
	v_mov_b32_e32 v89, v86
	v_mov_b32_e32 v80, v86
	v_mov_b32_e32 v81, v86
	v_mov_b32_e32 v76, v86
	v_mov_b32_e32 v77, v86
	v_mov_b32_e32 v82, v86
	v_mov_b32_e32 v83, v86
	v_mov_b32_e32 v78, v86
	v_mov_b32_e32 v79, v86
	v_mov_b32_e32 v72, v86
	v_mov_b32_e32 v73, v86
	v_mov_b32_e32 v68, v86
	v_mov_b32_e32 v69, v86
	v_mov_b32_e32 v74, v86
	v_mov_b32_e32 v75, v86
	v_mov_b32_e32 v70, v86
	v_mov_b32_e32 v71, v86
	v_mov_b32_e32 v64, v86
	v_mov_b32_e32 v65, v86
	v_mov_b32_e32 v60, v86
	v_mov_b32_e32 v61, v86
	v_mov_b32_e32 v66, v86
	v_mov_b32_e32 v67, v86
	v_mov_b32_e32 v62, v86
	v_mov_b32_e32 v63, v86
	v_lshl_add_u64 v[214:215], s[96:97], 0, v[94:95]
	s_mov_b32 s13, 0xe000000
	v_add_co_u32_e32 v214, vcc, s13, v214
	s_nop 1
	v_addc_co_u32_e32 v215, vcc, 0, v215, vcc
	global_load_dwordx4 v[204:207], v[214:215], off
	global_load_dwordx4 v[208:211], v[214:215], off offset:64
	v_lshl_add_u64 v[214:215], s[96:97], 0, v[92:93]
	global_load_ushort v212, v[214:215], off
	s_waitcnt lgkmcnt(0)
	s_barrier
	s_waitcnt vmcnt(0)
.LBB0_2008:
	s_nop 1
	v_add_u32_e32 v32, v100, v195
	ds_read_b128 v[16:19], v32 offset:2368
	s_waitcnt vmcnt(4)
	v_mov_b32_e32 v0, v204
	v_mov_b32_e32 v1, v205
	v_mov_b32_e32 v2, v206
	v_mov_b32_e32 v3, v207
	v_mov_b32_e32 v4, v208
	v_mov_b32_e32 v5, v209
	v_mov_b32_e32 v6, v210
	v_mov_b32_e32 v7, v211
	v_mov_b32_e32 v213, v212
	v_lshl_add_u64 v[214:215], s[96:97], 0, v[94:95]
	s_mov_b32 s13, 0xe000000
	v_lshl_add_u64 v[214:215], v[214:215], 0, s[10:11]
	v_add_co_u32_e32 v214, vcc, s13, v214
	s_nop 1
	v_addc_co_u32_e32 v215, vcc, 0, v215, vcc
	global_load_dwordx4 v[204:207], v[214:215], off
	global_load_dwordx4 v[208:211], v[214:215], off offset:64
	v_lshl_add_u64 v[214:215], s[96:97], 0, v[92:93]
	global_load_ushort v212, v[214:215], off offset:6
	v_lshlrev_b32_e32 v8, 16, v0
	v_lshlrev_b32_e32 v10, 16, v4
	v_and_b32_e32 v11, 0xffff0000, v4
	v_and_b32_e32 v9, 0xffff0000, v0
	v_pk_mul_f32 v[12:13], v[10:11], s[6:7] op_sel_hi:[1,0]
	v_lshlrev_b32_e32 v0, 16, v1
	v_and_b32_e32 v1, 0xffff0000, v1
	v_lshlrev_b32_e32 v4, 16, v5
	v_and_b32_e32 v5, 0xffff0000, v5
	v_lshlrev_b32_e32 v10, 16, v2
	v_and_b32_e32 v11, 0xffff0000, v2
	v_lshlrev_b32_e32 v14, 16, v6
	v_and_b32_e32 v15, 0xffff0000, v6
	v_lshlrev_b32_e32 v2, 16, v3
	v_and_b32_e32 v3, 0xffff0000, v3
	v_lshlrev_b32_e32 v6, 16, v7
	v_and_b32_e32 v7, 0xffff0000, v7
	v_pk_mul_f32 v[8:9], v[8:9], s[6:7] op_sel_hi:[1,0]
	v_pk_mul_f32 v[0:1], v[0:1], s[6:7] op_sel_hi:[1,0]
	v_pk_mul_f32 v[4:5], v[4:5], s[6:7] op_sel_hi:[1,0]
	v_pk_mul_f32 v[10:11], v[10:11], s[6:7] op_sel_hi:[1,0]
	v_pk_mul_f32 v[2:3], v[2:3], s[6:7] op_sel_hi:[1,0]
	v_pk_mul_f32 v[6:7], v[6:7], s[6:7] op_sel_hi:[1,0]
	v_cvt_pk_bf16_f32 v8, v8, v9
	v_cvt_pk_bf16_f32 v9, v0, v1
	v_cvt_pk_bf16_f32 v10, v10, v11
	v_cvt_pk_bf16_f32 v11, v2, v3
	v_cvt_pk_bf16_f32 v1, v4, v5
	v_cvt_pk_bf16_f32 v3, v6, v7
	ds_read_b128 v[4:7], v32
	v_pk_mul_f32 v[14:15], v[14:15], s[6:7] op_sel_hi:[1,0]
	v_cvt_pk_bf16_f32 v0, v12, v13
	v_cvt_pk_bf16_f32 v2, v14, v15
	ds_read_b128 v[12:15], v32 offset:64
	s_waitcnt lgkmcnt(1)
	v_mfma_f32_16x16x32_bf16 v[4:7], v[4:7], v[8:11], 0
	s_waitcnt lgkmcnt(0)
	v_mfma_f32_16x16x32_bf16 v[4:7], v[12:15], v[0:3], v[4:7]
	s_nop 7
	v_max_f32_e32 v12, v4, v4
	v_max_f32_e32 v12, 0xf149f2ca, v12
	v_cndmask_b32_e64 v12, v160, v12, s[24:25]
	v_max_f32_e32 v13, v5, v5
	v_max_f32_e32 v13, v12, v13
	v_cndmask_b32_e64 v12, v12, v13, s[26:27]
	v_max_f32_e32 v13, v6, v6
	v_max_f32_e32 v13, v12, v13
	v_cndmask_b32_e64 v12, v12, v13, s[28:29]
	v_max_f32_e32 v13, v7, v7
	v_max_f32_e32 v13, v12, v13
	v_cndmask_b32_e64 v20, v12, v13, s[30:31]
	ds_read_b128 v[12:15], v32 offset:2304
	s_waitcnt lgkmcnt(0)
	v_mfma_f32_16x16x32_bf16 v[12:15], v[12:15], v[8:11], 0
	v_mfma_f32_16x16x32_bf16 v[12:15], v[16:19], v[0:3], v[12:15]
	s_nop 7
	v_max_f32_e32 v16, v12, v12
	v_max_f32_e32 v16, v20, v16
	v_cndmask_b32_e64 v16, v20, v16, s[34:35]
	v_max_f32_e32 v17, v16, v16
	v_max_f32_e32 v18, v13, v13
	v_max_f32_e32 v17, v17, v18
	v_cndmask_b32_e64 v16, v16, v17, s[36:37]
	v_max_f32_e32 v17, v16, v16
	v_max_f32_e32 v18, v14, v14
	v_max_f32_e32 v17, v17, v18
	v_cndmask_b32_e64 v16, v16, v17, s[38:39]
	v_max_f32_e32 v17, v16, v16
	v_max_f32_e32 v18, v15, v15
	v_max_f32_e32 v17, v17, v18
	v_cndmask_b32_e64 v24, v16, v17, s[40:41]
	ds_read_b128 v[16:19], v32 offset:4608
	ds_read_b128 v[20:23], v32 offset:4672
	s_waitcnt lgkmcnt(1)
	v_mfma_f32_16x16x32_bf16 v[16:19], v[16:19], v[8:11], 0
	s_waitcnt lgkmcnt(0)
	v_mfma_f32_16x16x32_bf16 v[16:19], v[20:23], v[0:3], v[16:19]
	v_max_f32_e32 v20, v24, v24
	s_nop 6
	v_max_f32_e32 v21, v16, v16
	v_max_f32_e32 v20, v20, v21
	v_cndmask_b32_e64 v20, v24, v20, s[42:43]
	v_max_f32_e32 v21, v20, v20
	v_max_f32_e32 v22, v17, v17
	v_max_f32_e32 v21, v21, v22
	v_cndmask_b32_e64 v20, v20, v21, s[44:45]
	v_max_f32_e32 v21, v20, v20
	v_max_f32_e32 v22, v18, v18
	v_max_f32_e32 v21, v21, v22
	v_cndmask_b32_e64 v20, v20, v21, s[46:47]
	v_max_f32_e32 v21, v20, v20
	v_max_f32_e32 v22, v19, v19
	v_max_f32_e32 v21, v21, v22
	v_cndmask_b32_e64 v28, v20, v21, s[48:49]
	ds_read_b128 v[20:23], v151
	ds_read_b128 v[24:27], v151 offset:64
	s_waitcnt lgkmcnt(1)
	v_mfma_f32_16x16x32_bf16 v[20:23], v[20:23], v[8:11], 0
	s_waitcnt lgkmcnt(0)
	v_mfma_f32_16x16x32_bf16 v[20:23], v[24:27], v[0:3], v[20:23]
	v_max_f32_e32 v24, v28, v28
	s_nop 6
	v_max_f32_e32 v25, v20, v20
	v_max_f32_e32 v24, v24, v25
	v_cndmask_b32_e64 v24, v28, v24, s[50:51]
	v_max_f32_e32 v25, v24, v24
	v_max_f32_e32 v26, v21, v21
	v_max_f32_e32 v25, v25, v26
	v_cndmask_b32_e64 v24, v24, v25, s[52:53]
	v_max_f32_e32 v25, v24, v24
	v_max_f32_e32 v26, v22, v22
	v_max_f32_e32 v25, v25, v26
	v_cndmask_b32_e64 v24, v24, v25, s[54:55]
	v_max_f32_e32 v25, v24, v24
	v_max_f32_e32 v26, v23, v23
	v_max_f32_e32 v25, v25, v26
	v_cndmask_b32_e64 v33, v24, v25, s[56:57]
	ds_read_b128 v[24:27], v32 offset:9216
	ds_read_b128 v[28:31], v32 offset:9280
	s_waitcnt lgkmcnt(1)
	v_mfma_f32_16x16x32_bf16 v[24:27], v[24:27], v[8:11], 0
	ds_read_b128 v[162:165], v32 offset:11584
	s_waitcnt lgkmcnt(1)
	v_mfma_f32_16x16x32_bf16 v[24:27], v[28:31], v[0:3], v[24:27]
	v_max_f32_e32 v28, v33, v33
	s_nop 6
	v_max_f32_e32 v29, v24, v24
	v_max_f32_e32 v28, v28, v29
	v_cndmask_b32_e64 v28, v33, v28, s[58:59]
	v_max_f32_e32 v29, v28, v28
	v_max_f32_e32 v30, v25, v25
	v_max_f32_e32 v29, v29, v30
	v_cndmask_b32_e64 v28, v28, v29, s[60:61]
	v_max_f32_e32 v29, v28, v28
	v_max_f32_e32 v30, v26, v26
	v_max_f32_e32 v29, v29, v30
	v_cndmask_b32_e64 v28, v28, v29, s[62:63]
	v_max_f32_e32 v29, v28, v28
	v_max_f32_e32 v30, v27, v27
	v_max_f32_e32 v29, v29, v30
	v_cndmask_b32_e64 v33, v28, v29, s[64:65]
	ds_read_b128 v[28:31], v32 offset:11520
	s_waitcnt lgkmcnt(0)
	v_mfma_f32_16x16x32_bf16 v[28:31], v[28:31], v[8:11], 0
	v_max_f32_e32 v34, v33, v33
	v_mfma_f32_16x16x32_bf16 v[28:31], v[162:165], v[0:3], v[28:31]
	s_nop 7
	v_max_f32_e32 v35, v28, v28
	v_max_f32_e32 v34, v34, v35
	v_cndmask_b32_e64 v33, v33, v34, s[66:67]
	v_max_f32_e32 v34, v33, v33
	v_max_f32_e32 v35, v29, v29
	v_max_f32_e32 v34, v34, v35
	v_cndmask_b32_e64 v33, v33, v34, s[68:69]
	v_max_f32_e32 v34, v33, v33
	v_max_f32_e32 v35, v30, v30
	v_max_f32_e32 v34, v34, v35
	v_cndmask_b32_e64 v33, v33, v34, s[70:71]
	v_max_f32_e32 v34, v33, v33
	v_max_f32_e32 v35, v31, v31
	v_max_f32_e32 v34, v34, v35
	v_cndmask_b32_e64 v36, v33, v34, s[72:73]
	ds_read_b128 v[162:165], v32 offset:13824
	ds_read_b128 v[32:35], v32 offset:13888
	v_max_f32_e32 v55, v36, v36
	s_waitcnt lgkmcnt(1)
	v_mfma_f32_16x16x32_bf16 v[162:165], v[162:165], v[8:11], 0
	s_waitcnt lgkmcnt(0)
	v_mfma_f32_16x16x32_bf16 v[32:35], v[32:35], v[0:3], v[162:165]
	s_nop 5
	ds_read_b128 v[162:165], v157
	s_waitcnt lgkmcnt(0)
	v_mfma_f32_16x16x32_bf16 v[8:11], v[162:165], v[8:11], 0
	ds_read_b128 v[162:165], v157 offset:64
	v_max_f32_e32 v57, v32, v32
	v_max_f32_e32 v55, v55, v57
	v_cndmask_b32_e64 v36, v36, v55, s[74:75]
	v_max_f32_e32 v55, v36, v36
	v_max_f32_e32 v57, v33, v33
	v_max_f32_e32 v55, v55, v57
	v_cndmask_b32_e64 v36, v36, v55, s[76:77]
	v_max_f32_e32 v55, v36, v36
	v_max_f32_e32 v57, v34, v34
	v_max_f32_e32 v55, v55, v57
	v_cndmask_b32_e64 v36, v36, v55, s[78:79]
	s_waitcnt lgkmcnt(0)
	v_mfma_f32_16x16x32_bf16 v[0:3], v[162:165], v[0:3], v[8:11]
	v_max_f32_e32 v55, v36, v36
	v_max_f32_e32 v57, v35, v35
	v_max_f32_e32 v55, v55, v57
	v_cndmask_b32_e64 v36, v36, v55, s[80:81]
	v_max_f32_e32 v8, v36, v36
	s_nop 2
	v_max_f32_e32 v9, v0, v0
	v_max_f32_e32 v8, v8, v9
	v_cndmask_b32_e64 v8, v36, v8, s[82:83]
	v_max_f32_e32 v9, v8, v8
	v_max_f32_e32 v10, v1, v1
	v_max_f32_e32 v9, v9, v10
	v_cndmask_b32_e64 v8, v8, v9, s[84:85]
	v_max_f32_e32 v9, v8, v8
	v_max_f32_e32 v10, v2, v2
	v_max_f32_e32 v9, v9, v10
	v_cndmask_b32_e64 v8, v8, v9, s[86:87]
	v_max_f32_e32 v9, v8, v8
	v_max_f32_e32 v10, v3, v3
	v_max_f32_e32 v9, v9, v10
	v_cndmask_b32_e64 v8, v8, v9, s[88:89]
	v_mov_b32_e32 v9, v8
	s_nop 1
	v_permlane16_swap_b32_e32 v8, v9
	v_max_f32_e32 v9, v9, v9
	v_max_f32_e32 v8, v8, v8
	v_max_f32_e32 v8, v8, v9
	v_mov_b32_e32 v9, v8
	s_nop 1
	v_permlane32_swap_b32_e32 v8, v9
	v_max_f32_e32 v9, v9, v9
	v_max_f32_e32 v8, v8, v8
	v_max_f32_e32 v8, v8, v9
	v_sub_f32_e32 v4, v4, v8
	v_mul_f32_e32 v4, 0x3fb8aa3b, v4
	v_sub_f32_e32 v5, v5, v8
	v_exp_f32_e32 v4, v4
	v_mul_f32_e32 v5, 0x3fb8aa3b, v5
	v_sub_f32_e32 v6, v6, v8
	v_exp_f32_e32 v5, v5
	v_mul_f32_e32 v6, 0x3fb8aa3b, v6
	v_sub_f32_e32 v7, v7, v8
	v_exp_f32_e32 v6, v6
	v_mul_f32_e32 v7, 0x3fb8aa3b, v7
	v_sub_f32_e32 v10, v12, v8
	v_exp_f32_e32 v7, v7
	v_mul_f32_e32 v10, 0x3fb8aa3b, v10
	v_sub_f32_e32 v11, v13, v8
	v_cndmask_b32_e64 v4, 0, v4, s[24:25]
	v_exp_f32_e32 v10, v10
	v_mul_f32_e32 v11, 0x3fb8aa3b, v11
	v_sub_f32_e32 v12, v14, v8
	v_add_f32_e32 v9, 0, v4
	v_cndmask_b32_e64 v5, 0, v5, s[26:27]
	v_exp_f32_e32 v11, v11
	v_mul_f32_e32 v12, 0x3fb8aa3b, v12
	v_sub_f32_e32 v13, v15, v8
	v_add_f32_e32 v9, v5, v9
	v_cndmask_b32_e64 v6, 0, v6, s[28:29]
	v_exp_f32_e32 v12, v12
	v_mul_f32_e32 v13, 0x3fb8aa3b, v13
	v_sub_f32_e32 v14, v16, v8
	v_add_f32_e32 v9, v6, v9
	v_cndmask_b32_e64 v7, 0, v7, s[30:31]
	v_exp_f32_e32 v13, v13
	v_mul_f32_e32 v14, 0x3fb8aa3b, v14
	v_sub_f32_e32 v15, v17, v8
	v_add_f32_e32 v9, v7, v9
	v_cndmask_b32_e64 v10, 0, v10, s[34:35]
	v_exp_f32_e32 v14, v14
	v_mul_f32_e32 v15, 0x3fb8aa3b, v15
	v_sub_f32_e32 v16, v18, v8
	v_add_f32_e32 v9, v10, v9
	v_cndmask_b32_e64 v11, 0, v11, s[36:37]
	v_exp_f32_e32 v15, v15
	v_mul_f32_e32 v16, 0x3fb8aa3b, v16
	v_sub_f32_e32 v17, v19, v8
	v_add_f32_e32 v9, v11, v9
	v_cndmask_b32_e64 v12, 0, v12, s[38:39]
	v_exp_f32_e32 v16, v16
	v_mul_f32_e32 v17, 0x3fb8aa3b, v17
	v_sub_f32_e32 v18, v20, v8
	v_add_f32_e32 v9, v12, v9
	v_cndmask_b32_e64 v13, 0, v13, s[40:41]
	v_exp_f32_e32 v17, v17
	v_mul_f32_e32 v18, 0x3fb8aa3b, v18
	v_sub_f32_e32 v19, v21, v8
	v_add_f32_e32 v9, v13, v9
	v_cndmask_b32_e64 v14, 0, v14, s[42:43]
	v_exp_f32_e32 v18, v18
	v_mul_f32_e32 v19, 0x3fb8aa3b, v19
	v_sub_f32_e32 v20, v22, v8
	v_add_f32_e32 v9, v14, v9
	v_cndmask_b32_e64 v15, 0, v15, s[44:45]
	v_exp_f32_e32 v19, v19
	v_mul_f32_e32 v20, 0x3fb8aa3b, v20
	v_sub_f32_e32 v21, v23, v8
	v_add_f32_e32 v9, v15, v9
	v_cndmask_b32_e64 v16, 0, v16, s[46:47]
	v_exp_f32_e32 v20, v20
	v_mul_f32_e32 v21, 0x3fb8aa3b, v21
	v_sub_f32_e32 v22, v24, v8
	v_add_f32_e32 v9, v16, v9
	v_cndmask_b32_e64 v17, 0, v17, s[48:49]
	v_exp_f32_e32 v21, v21
	v_mul_f32_e32 v22, 0x3fb8aa3b, v22
	v_sub_f32_e32 v23, v25, v8
	v_add_f32_e32 v9, v17, v9
	v_cndmask_b32_e64 v18, 0, v18, s[50:51]
	v_exp_f32_e32 v22, v22
	v_mul_f32_e32 v23, 0x3fb8aa3b, v23
	v_sub_f32_e32 v24, v26, v8
	v_add_f32_e32 v9, v18, v9
	v_cndmask_b32_e64 v19, 0, v19, s[52:53]
	v_exp_f32_e32 v23, v23
	v_mul_f32_e32 v24, 0x3fb8aa3b, v24
	v_sub_f32_e32 v25, v27, v8
	v_sub_f32_e32 v1, v1, v8
	v_add_f32_e32 v9, v19, v9
	v_cndmask_b32_e64 v20, 0, v20, s[54:55]
	v_exp_f32_e32 v24, v24
	v_mul_f32_e32 v25, 0x3fb8aa3b, v25
	v_sub_f32_e32 v26, v28, v8
	v_mul_f32_e32 v1, 0x3fb8aa3b, v1
	v_add_f32_e32 v9, v20, v9
	v_cndmask_b32_e64 v21, 0, v21, s[56:57]
	v_exp_f32_e32 v25, v25
	v_mul_f32_e32 v26, 0x3fb8aa3b, v26
	v_sub_f32_e32 v27, v29, v8
	v_exp_f32_e32 v1, v1
	v_add_f32_e32 v9, v21, v9
	v_cndmask_b32_e64 v22, 0, v22, s[58:59]
	v_exp_f32_e32 v26, v26
	v_mul_f32_e32 v27, 0x3fb8aa3b, v27
	v_sub_f32_e32 v28, v30, v8
	v_add_f32_e32 v9, v22, v9
	v_cndmask_b32_e64 v23, 0, v23, s[60:61]
	v_exp_f32_e32 v27, v27
	v_mul_f32_e32 v28, 0x3fb8aa3b, v28
	v_sub_f32_e32 v29, v31, v8
	v_add_f32_e32 v9, v23, v9
	v_cndmask_b32_e64 v24, 0, v24, s[62:63]
	v_exp_f32_e32 v28, v28
	v_mul_f32_e32 v29, 0x3fb8aa3b, v29
	v_sub_f32_e32 v30, v32, v8
	v_add_f32_e32 v9, v24, v9
	v_cndmask_b32_e64 v25, 0, v25, s[64:65]
	v_exp_f32_e32 v29, v29
	v_mul_f32_e32 v30, 0x3fb8aa3b, v30
	v_sub_f32_e32 v31, v33, v8
	v_sub_f32_e32 v33, v35, v8
	v_cndmask_b32_e64 v35, 0, v1, s[84:85]
	v_sub_f32_e32 v1, v2, v8
	v_add_f32_e32 v9, v25, v9
	v_cndmask_b32_e64 v26, 0, v26, s[66:67]
	v_exp_f32_e32 v30, v30
	v_mul_f32_e32 v31, 0x3fb8aa3b, v31
	v_sub_f32_e32 v32, v34, v8
	v_mul_f32_e32 v1, 0x3fb8aa3b, v1
	v_add_f32_e32 v9, v26, v9
	v_cndmask_b32_e64 v27, 0, v27, s[68:69]
	v_exp_f32_e32 v31, v31
	v_mul_f32_e32 v32, 0x3fb8aa3b, v32
	v_exp_f32_e32 v1, v1
	v_add_f32_e32 v9, v27, v9
	v_cndmask_b32_e64 v28, 0, v28, s[70:71]
	v_exp_f32_e32 v32, v32
	v_mul_f32_e32 v33, 0x3fb8aa3b, v33
	v_sub_f32_e32 v0, v0, v8
	v_add_f32_e32 v9, v28, v9
	v_cndmask_b32_e64 v29, 0, v29, s[72:73]
	v_exp_f32_e32 v33, v33
	v_mul_f32_e32 v0, 0x3fb8aa3b, v0
	v_add_f32_e32 v9, v29, v9
	v_cndmask_b32_e64 v30, 0, v30, s[74:75]
	v_exp_f32_e32 v0, v0
	v_add_f32_e32 v9, v30, v9
	v_cndmask_b32_e64 v31, 0, v31, s[76:77]
	v_cndmask_b32_e64 v162, 0, v1, s[86:87]
	v_sub_f32_e32 v1, v3, v8
	v_add_f32_e32 v9, v31, v9
	v_cndmask_b32_e64 v32, 0, v32, s[78:79]
	v_mul_f32_e32 v1, 0x3fb8aa3b, v1
	v_add_f32_e32 v9, v32, v9
	v_cndmask_b32_e64 v33, 0, v33, s[80:81]
	v_exp_f32_e32 v1, v1
	v_add_f32_e32 v9, v33, v9
	v_cndmask_b32_e64 v34, 0, v0, s[82:83]
	v_add_f32_e32 v0, v34, v9
	v_add_f32_e32 v0, v35, v0
	v_add_f32_e32 v0, v162, v0
	v_cndmask_b32_e64 v163, 0, v1, s[88:89]
	v_add_f32_e32 v0, v163, v0
	v_mov_b32_e32 v1, v0
	s_nop 1
	v_permlane16_swap_b32_e32 v0, v1
	v_add_f32_e32 v0, v0, v1
	v_mov_b32_e32 v1, v0
	s_nop 1
	v_permlane32_swap_b32_e32 v0, v1
	v_add_f32_e32 v0, v0, v1
	v_max_f32_e32 v0, 0xda24260, v0
	v_div_scale_f32 v1, vcc, v0, v0, 1.0
	v_rcp_f32_e32 v2, v1
	s_add_i32 s0, s0, -1
	v_lshl_add_u64 v[94:95], v[94:95], 0, s[10:11]
	s_cmp_eq_u32 s0, 0
	v_fma_f32 v3, -v1, v2, 1.0
	v_fmac_f32_e32 v2, v3, v2
	v_div_scale_f32 v3, vcc, 1.0, v0, 1.0
	v_mul_f32_e32 v8, v3, v2
	v_fma_f32 v9, -v1, v8, v3
	v_fmac_f32_e32 v8, v9, v2
	v_fma_f32 v1, -v1, v8, v3
	v_div_fmas_f32 v1, v1, v2, v8
	v_div_fixup_f32 v36, v1, v0, 1.0
	v_pk_mul_f32 v[2:3], v[36:37], v[6:7] op_sel_hi:[0,1]
	v_pk_fma_f32 v[84:85], v[36:37], v[6:7], v[84:85] op_sel_hi:[0,1,1]
	v_pk_mul_f32 v[6:7], v[36:37], v[16:17] op_sel_hi:[0,1]
	v_pk_fma_f32 v[76:77], v[36:37], v[16:17], v[76:77] op_sel_hi:[0,1,1]
	v_pk_mul_f32 v[16:17], v[36:37], v[18:19] op_sel_hi:[0,1]
	v_pk_fma_f32 v[82:83], v[36:37], v[18:19], v[82:83] op_sel_hi:[0,1,1]
	v_pk_mul_f32 v[18:19], v[36:37], v[22:23] op_sel_hi:[0,1]
	v_pk_fma_f32 v[72:73], v[36:37], v[22:23], v[72:73] op_sel_hi:[0,1,1]
	v_pk_mul_f32 v[22:23], v[36:37], v[32:33] op_sel_hi:[0,1]
	v_pk_fma_f32 v[60:61], v[36:37], v[32:33], v[60:61] op_sel_hi:[0,1,1]
	v_mov_b32_e32 v32, v213
	v_add_u32_e32 v33, 0x4800, v158
	v_pk_mul_f32 v[0:1], v[36:37], v[4:5] op_sel_hi:[0,1]
	v_pk_fma_f32 v[86:87], v[36:37], v[4:5], v[86:87] op_sel_hi:[0,1,1]
	v_pk_mul_f32 v[4:5], v[36:37], v[12:13] op_sel_hi:[0,1]
	v_pk_fma_f32 v[88:89], v[36:37], v[12:13], v[88:89] op_sel_hi:[0,1,1]
	v_pk_mul_f32 v[12:13], v[36:37], v[20:21] op_sel_hi:[0,1]
	v_pk_fma_f32 v[78:79], v[36:37], v[20:21], v[78:79] op_sel_hi:[0,1,1]
	v_pk_mul_f32 v[20:21], v[36:37], v[28:29] op_sel_hi:[0,1]
	v_pk_fma_f32 v[70:71], v[36:37], v[28:29], v[70:71] op_sel_hi:[0,1,1]
	v_pk_mul_f32 v[28:29], v[36:37], v[162:163] op_sel_hi:[0,1]
	v_pk_fma_f32 v[62:63], v[36:37], v[162:163], v[62:63] op_sel_hi:[0,1,1]
	ds_read2_b64 v[162:165], v33 offset1:4
	ds_read2_b64 v[166:169], v33 offset0:8 offset1:12
	v_pk_mul_f32 v[8:9], v[36:37], v[10:11] op_sel_hi:[0,1]
	v_cvt_pk_bf16_f32 v0, v0, v1
	v_cvt_pk_bf16_f32 v1, v2, v3
	v_cvt_pk_bf16_f32 v2, v8, v9
	v_cvt_pk_bf16_f32 v3, v4, v5
	v_pk_fma_f32 v[90:91], v[36:37], v[10:11], v[90:91] op_sel_hi:[0,1,1]
	v_pk_mul_f32 v[10:11], v[36:37], v[14:15] op_sel_hi:[0,1]
	s_waitcnt lgkmcnt(1)
	v_mfma_f32_16x16x32_bf16 v[162:165], v[162:165], v[0:3], 0
	v_cvt_pk_bf16_f32 v4, v10, v11
	v_cvt_pk_bf16_f32 v5, v6, v7
	v_cvt_pk_bf16_f32 v6, v16, v17
	v_cvt_pk_bf16_f32 v7, v12, v13
	v_pk_fma_f32 v[80:81], v[36:37], v[14:15], v[80:81] op_sel_hi:[0,1,1]
	v_pk_mul_f32 v[14:15], v[36:37], v[24:25] op_sel_hi:[0,1]
	s_waitcnt lgkmcnt(0)
	v_mfma_f32_16x16x32_bf16 v[162:165], v[166:169], v[4:7], v[162:165]
	ds_read2_b64 v[166:169], v33 offset0:16 offset1:20
	v_pk_fma_f32 v[68:69], v[36:37], v[24:25], v[68:69] op_sel_hi:[0,1,1]
	v_pk_mul_f32 v[24:25], v[36:37], v[26:27] op_sel_hi:[0,1]
	v_cvt_pk_bf16_f32 v8, v18, v19
	v_cvt_pk_bf16_f32 v9, v14, v15
	v_cvt_pk_bf16_f32 v10, v24, v25
	v_cvt_pk_bf16_f32 v11, v20, v21
	v_pk_fma_f32 v[74:75], v[36:37], v[26:27], v[74:75] op_sel_hi:[0,1,1]
	v_pk_mul_f32 v[26:27], v[36:37], v[30:31] op_sel_hi:[0,1]
	s_waitcnt lgkmcnt(0)
	v_mfma_f32_16x16x32_bf16 v[16:19], v[166:169], v[8:11], v[162:165]
	v_fma_f32 v64, v36, v30, v64
	v_fma_f32 v65, v36, v31, v65
	v_pk_mul_f32 v[30:31], v[36:37], v[34:35] op_sel_hi:[0,1]
	v_cvt_pk_bf16_f32 v12, v26, v27
	ds_read2_b64 v[162:165], v33 offset0:24 offset1:28
	v_cvt_pk_bf16_f32 v13, v22, v23
	v_cvt_pk_bf16_f32 v14, v30, v31
	v_cvt_pk_bf16_f32 v15, v28, v29
	v_pk_fma_f32 v[66:67], v[36:37], v[34:35], v[66:67] op_sel_hi:[0,1,1]
	v_lshl_add_u64 v[34:35], s[96:97], 0, v[96:97]
	s_waitcnt lgkmcnt(0)
	v_mfma_f32_16x16x32_bf16 v[16:19], v[162:165], v[12:15], v[16:19]
	v_add_u32_e32 v24, 0x5800, v158
	ds_read2_b64 v[20:23], v24 offset0:40 offset1:44
	v_lshl_add_u64 v[92:93], v[92:93], 0, 6
	v_lshl_add_u64 v[96:97], v[96:97], 0, s[10:11]
	v_lshlrev_b32_e32 v32, 16, v32
	s_nop 1
	v_pk_mul_f32 v[16:17], v[16:17], v[32:33] op_sel_hi:[1,0]
	v_pk_mul_f32 v[18:19], v[18:19], v[32:33] op_sel_hi:[1,0]
	v_cvt_pk_bf16_f32 v16, v16, v17
	v_cvt_pk_bf16_f32 v17, v18, v19
	global_store_dwordx2 v[34:35], v[16:17], off offset:-64
	ds_read2_b64 v[16:19], v24 offset0:32 offset1:36
	s_waitcnt lgkmcnt(0)
	v_mfma_f32_16x16x32_bf16 v[16:19], v[16:19], v[0:3], 0
	v_mfma_f32_16x16x32_bf16 v[16:19], v[20:23], v[4:7], v[16:19]
	ds_read2_b64 v[20:23], v24 offset0:48 offset1:52
	s_waitcnt lgkmcnt(0)
	v_mfma_f32_16x16x32_bf16 v[16:19], v[20:23], v[8:11], v[16:19]
	ds_read2_b64 v[20:23], v24 offset0:56 offset1:60
	v_add_u32_e32 v24, 0x6800, v158
	s_waitcnt lgkmcnt(0)
	v_mfma_f32_16x16x32_bf16 v[16:19], v[20:23], v[12:15], v[16:19]
	ds_read2_b64 v[20:23], v24 offset0:72 offset1:76
	s_nop 6
	v_pk_mul_f32 v[16:17], v[16:17], v[32:33] op_sel_hi:[1,0]
	v_pk_mul_f32 v[18:19], v[18:19], v[32:33] op_sel_hi:[1,0]
	v_cvt_pk_bf16_f32 v16, v16, v17
	v_cvt_pk_bf16_f32 v17, v18, v19
	global_store_dwordx2 v[34:35], v[16:17], off offset:-32
	ds_read2_b64 v[16:19], v24 offset0:64 offset1:68
	s_waitcnt lgkmcnt(0)
	v_mfma_f32_16x16x32_bf16 v[16:19], v[16:19], v[0:3], 0
	v_mfma_f32_16x16x32_bf16 v[16:19], v[20:23], v[4:7], v[16:19]
	ds_read2_b64 v[20:23], v24 offset0:80 offset1:84
	s_waitcnt lgkmcnt(0)
	v_mfma_f32_16x16x32_bf16 v[16:19], v[20:23], v[8:11], v[16:19]
	ds_read2_b64 v[20:23], v24 offset0:88 offset1:92
	s_waitcnt lgkmcnt(0)
	v_mfma_f32_16x16x32_bf16 v[16:19], v[20:23], v[12:15], v[16:19]
	v_add_u32_e32 v20, 0x4800, v159
	s_nop 6
	v_pk_mul_f32 v[16:17], v[16:17], v[32:33] op_sel_hi:[1,0]
	v_pk_mul_f32 v[18:19], v[18:19], v[32:33] op_sel_hi:[1,0]
	v_cvt_pk_bf16_f32 v16, v16, v17
	v_cvt_pk_bf16_f32 v17, v18, v19
	global_store_dwordx2 v[34:35], v[16:17], off
	ds_read2_b64 v[16:19], v20 offset1:4
	s_waitcnt lgkmcnt(0)
	v_mfma_f32_16x16x32_bf16 v[0:3], v[16:19], v[0:3], 0
	ds_read2_b64 v[16:19], v20 offset0:8 offset1:12
	s_waitcnt lgkmcnt(0)
	v_mfma_f32_16x16x32_bf16 v[0:3], v[16:19], v[4:7], v[0:3]
	ds_read2_b64 v[4:7], v20 offset0:16 offset1:20
	s_waitcnt lgkmcnt(0)
	v_mfma_f32_16x16x32_bf16 v[0:3], v[4:7], v[8:11], v[0:3]
	ds_read2_b64 v[4:7], v20 offset0:24 offset1:28
	s_waitcnt lgkmcnt(0)
	v_mfma_f32_16x16x32_bf16 v[0:3], v[4:7], v[12:15], v[0:3]
	s_nop 7
	v_pk_mul_f32 v[0:1], v[0:1], v[32:33] op_sel_hi:[1,0]
	v_pk_mul_f32 v[2:3], v[2:3], v[32:33] op_sel_hi:[1,0]
	v_cvt_pk_bf16_f32 v0, v0, v1
	v_cvt_pk_bf16_f32 v1, v2, v3
	global_store_dwordx2 v[34:35], v[0:1], off offset:32
	s_cbranch_scc0 .LBB0_2008
	ds_bpermute_b32 v0, v141, v85
	ds_bpermute_b32 v6, v141, v89
	v_mov_b32_e32 v2, v90
	v_mov_b32_e32 v3, v86
	s_lshr_b32 s13, s1, 6
	s_waitcnt lgkmcnt(1)
	v_mul_f32_e32 v1, 0.5, v0
	s_waitcnt lgkmcnt(0)
	v_cndmask_b32_e64 v0, v6, v0, s[2:3]
	v_cndmask_b32_e64 v1, v1, 0, s[2:3]
	v_mul_f32_e32 v0, 0.5, v0
	v_pk_add_f32 v[0:1], v[2:3], v[0:1]
	v_mov_b32_e32 v86, v91
	s_add_i32 s15, s13, -1
	v_pk_add_f32 v[0:1], v[86:87], v[0:1]
	v_mov_b32_e32 v2, v88
	v_mov_b32_e32 v3, v84
	v_cmp_eq_u32_e32 vcc, s13, v39
	v_cmp_eq_u32_e64 s[0:1], s15, v39
	v_pk_add_f32 v[0:1], v[2:3], v[0:1]
	v_mov_b32_e32 v84, v89
	s_or_b64 s[26:27], vcc, s[0:1]
	v_pk_fma_f32 v[0:1], v[84:85], 0.5, v[0:1] op_sel_hi:[1,0,1]
	v_cmp_ge_u32_e64 s[24:25], s13, v39
	v_cmp_eq_u32_e32 vcc, s13, v38
	v_cmp_eq_u32_e64 s[0:1], s15, v38
	v_cndmask_b32_e64 v1, -1.0, v1, s[24:25]
	s_or_b64 s[24:25], s[2:3], s[26:27]
	v_cndmask_b32_e64 v1, v1, v161, s[24:25]
	ds_bpermute_b32 v55, v142, v1
	ds_bpermute_b32 v84, v143, v1
	v_cmp_ge_u32_e64 s[24:25], s13, v38
	s_or_b64 vcc, vcc, s[0:1]
	v_readlane_b32 s16, v251, 41
	v_cndmask_b32_e64 v0, -1.0, v0, s[24:25]
	s_waitcnt lgkmcnt(1)
	v_cmp_eq_f32_e64 s[0:1], v1, v55
	v_cndmask_b32_e32 v0, v0, v161, vcc
	v_cmp_lt_f32_e32 vcc, v1, v55
	s_and_b64 s[0:1], s[4:5], s[0:1]
	s_or_b64 s[0:1], vcc, s[0:1]
	ds_bpermute_b32 v86, v144, v1
	v_cndmask_b32_e64 v3, 0, 1, s[0:1]
	s_waitcnt lgkmcnt(1)
	v_cmp_eq_f32_e64 s[0:1], v1, v84
	v_readlane_b32 s17, v251, 42
	v_cmp_lt_f32_e32 vcc, v1, v84
	s_and_b64 s[0:1], s[16:17], s[0:1]
	s_or_b64 s[0:1], vcc, s[0:1]
	v_cmp_le_f32_e32 vcc, v0, v84
	ds_bpermute_b32 v9, v145, v1
	ds_bpermute_b32 v85, v142, v0
	v_cndmask_b32_e64 v2, 0, 1, vcc
	v_cmp_le_f32_e32 vcc, v0, v55
	s_waitcnt lgkmcnt(2)
	v_cmp_eq_f32_e64 s[24:25], v1, v86
	s_and_b64 s[24:25], s[8:9], s[24:25]
	v_addc_co_u32_e32 v2, vcc, 0, v2, vcc
	v_cmp_lt_f32_e32 vcc, v1, v86
	s_or_b64 s[24:25], vcc, s[24:25]
	v_cmp_le_f32_e32 vcc, v0, v86
	ds_bpermute_b32 v15, v141, v77
	ds_bpermute_b32 v27, v141, v79
	v_cndmask_b32_e64 v5, 0, 1, vcc
	s_waitcnt lgkmcnt(3)
	v_cmp_le_f32_e32 vcc, v0, v9
	ds_bpermute_b32 v13, v143, v0
	v_cndmask_b32_e64 v4, 0, 1, s[0:1]
	v_addc_co_u32_e32 v2, vcc, v2, v5, vcc
	s_waitcnt lgkmcnt(3)
	v_cmp_eq_f32_e64 s[0:1], v0, v85
	v_cmp_lt_f32_e32 vcc, v1, v85
	s_and_b64 s[0:1], s[4:5], s[0:1]
	ds_bpermute_b32 v87, v144, v0
	v_cndmask_b32_e64 v10, 0, 1, vcc
	v_cmp_lt_f32_e32 vcc, v0, v85
	s_or_b64 s[0:1], vcc, s[0:1]
	v_readlane_b32 s16, v251, 52
	v_cndmask_b32_e64 v5, 0, 1, s[0:1]
	s_waitcnt lgkmcnt(1)
	v_cmp_eq_f32_e64 s[0:1], v0, v13
	v_readlane_b32 s17, v251, 53
	v_cndmask_b32_e64 v17, v15, v6, s[2:3]
	v_cndmask_b32_e64 v16, v27, v15, s[2:3]
	v_mov_b32_e32 v18, v82
	v_mov_b32_e32 v19, v80
	v_cmp_lt_f32_e32 vcc, v0, v13
	s_and_b64 s[0:1], s[0:1], s[16:17]
	v_pk_fma_f32 v[16:17], v[16:17], 0.5, v[18:19] op_sel_hi:[1,0,1]
	v_mov_b32_e32 v80, v83
	s_or_b64 s[0:1], vcc, s[0:1]
	v_pk_add_f32 v[16:17], v[80:81], v[16:17]
	v_mov_b32_e32 v18, v78
	v_mov_b32_e32 v19, v76
	v_cndmask_b32_e64 v7, 0, 1, s[0:1]
	s_waitcnt lgkmcnt(0)
	v_cmp_lt_f32_e32 vcc, v1, v87
	v_cmp_eq_f32_e64 s[0:1], v0, v87
	v_pk_add_f32 v[16:17], v[18:19], v[16:17]
	v_mov_b32_e32 v76, v79
	v_cndmask_b32_e64 v14, 0, 1, vcc
	v_cmp_lt_f32_e32 vcc, v0, v87
	s_and_b64 s[0:1], s[8:9], s[0:1]
	v_pk_fma_f32 v[16:17], v[76:77], 0.5, v[16:17] op_sel_hi:[1,0,1]
	v_cmp_ge_u32_e64 s[28:29], s13, v45
	v_cndmask_b32_e64 v8, 0, 1, s[24:25]
	s_or_b64 s[0:1], vcc, s[0:1]
	v_cmp_eq_u32_e32 vcc, s13, v44
	v_cmp_eq_u32_e64 s[24:25], s15, v44
	v_cndmask_b32_e64 v6, -1.0, v17, s[28:29]
	v_cmp_ge_u32_e64 s[28:29], s13, v44
	v_add_u32_e32 v5, v2, v5
	v_cndmask_b32_e64 v11, 0, 1, s[0:1]
	v_cmp_eq_u32_e64 s[0:1], s13, v45
	v_cmp_eq_u32_e64 s[26:27], s15, v45
	v_cndmask_b32_e64 v2, -1.0, v16, s[28:29]
	s_or_b64 vcc, vcc, s[24:25]
	v_cndmask_b32_e32 v2, v2, v161, vcc
	s_or_b64 vcc, s[0:1], s[26:27]
	v_cndmask_b32_e32 v6, v6, v161, vcc
	v_cmp_le_f32_e32 vcc, v6, v84
	ds_bpermute_b32 v12, v145, v0
	ds_bpermute_b32 v80, v142, v6
	v_cndmask_b32_e64 v15, 0, 1, vcc
	v_cmp_le_f32_e32 vcc, v6, v55
	v_readlane_b32 s16, v251, 54
	ds_bpermute_b32 v81, v144, v6
	v_addc_co_u32_e32 v15, vcc, 0, v15, vcc
	v_cmp_le_f32_e32 vcc, v2, v84
	s_waitcnt lgkmcnt(1)
	v_cmp_eq_f32_e64 s[0:1], v6, v80
	s_and_b64 s[0:1], s[4:5], s[0:1]
	v_cndmask_b32_e64 v16, 0, 1, vcc
	v_cmp_le_f32_e32 vcc, v2, v55
	v_readlane_b32 s17, v251, 55
	ds_bpermute_b32 v21, v145, v6
	v_addc_co_u32_e32 v16, vcc, 0, v16, vcc
	v_cmp_le_f32_e32 vcc, v6, v86
	ds_bpermute_b32 v82, v142, v2
	s_waitcnt lgkmcnt(2)
	v_cmp_eq_f32_e64 s[24:25], v6, v81
	v_cndmask_b32_e64 v17, 0, 1, vcc
	v_cmp_le_f32_e32 vcc, v2, v86
	s_and_b64 s[24:25], s[8:9], s[24:25]
	ds_bpermute_b32 v26, v143, v2
	v_cndmask_b32_e64 v18, 0, 1, vcc
	v_cmp_le_f32_e32 vcc, v6, v9
	ds_bpermute_b32 v31, v141, v69
	ds_bpermute_b32 v57, v141, v71
	v_addc_co_u32_e32 v15, vcc, v15, v17, vcc
	v_cmp_le_f32_e32 vcc, v2, v9
	ds_bpermute_b32 v83, v144, v2
	s_waitcnt lgkmcnt(2)
	v_cndmask_b32_e64 v77, v31, v27, s[2:3]
	v_addc_co_u32_e32 v16, vcc, v16, v18, vcc
	v_cmp_le_f32_e32 vcc, v6, v85
	s_waitcnt lgkmcnt(1)
	v_cndmask_b32_e64 v76, v57, v31, s[2:3]
	v_mov_b32_e32 v78, v74
	v_cndmask_b32_e64 v17, 0, 1, vcc
	v_cmp_le_f32_e32 vcc, v2, v85
	v_mov_b32_e32 v79, v72
	v_pk_fma_f32 v[76:77], v[76:77], 0.5, v[78:79] op_sel_hi:[1,0,1]
	v_cndmask_b32_e64 v18, 0, 1, vcc
	v_cmp_le_f32_e32 vcc, v6, v13
	v_mov_b32_e32 v72, v75
	v_pk_add_f32 v[72:73], v[72:73], v[76:77]
	v_addc_co_u32_e32 v15, vcc, v15, v17, vcc
	v_cmp_le_f32_e32 vcc, v2, v13
	v_mov_b32_e32 v74, v70
	v_mov_b32_e32 v75, v68
	v_addc_co_u32_e32 v16, vcc, v16, v18, vcc
	v_cmp_le_f32_e32 vcc, v6, v87
	v_pk_add_f32 v[72:73], v[74:75], v[72:73]
	v_mov_b32_e32 v68, v71
	v_cndmask_b32_e64 v17, 0, 1, vcc
	v_cmp_le_f32_e32 vcc, v2, v87
	v_pk_fma_f32 v[68:69], v[68:69], 0.5, v[72:73] op_sel_hi:[1,0,1]
	v_cmp_ge_u32_e64 s[28:29], s13, v47
	v_cndmask_b32_e64 v18, 0, 1, vcc
	v_cmp_le_f32_e32 vcc, v6, v12
	v_cndmask_b32_e64 v31, -1.0, v69, s[28:29]
	v_cmp_ge_u32_e64 s[28:29], s13, v46
	v_addc_co_u32_e32 v15, vcc, v15, v17, vcc
	v_cmp_le_f32_e32 vcc, v2, v12
	v_cmp_eq_u32_e64 s[26:27], s15, v47
	v_cndmask_b32_e64 v27, -1.0, v68, s[28:29]
	v_addc_co_u32_e32 v19, vcc, v16, v18, vcc
	ds_bpermute_b32 v18, v143, v6
	v_cmp_lt_f32_e32 vcc, v1, v80
	ds_bpermute_b32 v29, v145, v2
	ds_bpermute_b32 v59, v141, v61
	v_cndmask_b32_e64 v22, 0, 1, vcc
	v_cmp_lt_f32_e32 vcc, v0, v80
	ds_bpermute_b32 v92, v141, v63
	v_cmp_ge_u32_e64 s[28:29], s13, v49
	v_cndmask_b32_e64 v17, 0, 1, vcc
	v_cmp_lt_f32_e32 vcc, v6, v80
	s_or_b64 s[0:1], vcc, s[0:1]
	v_cndmask_b32_e64 v16, 0, 1, s[0:1]
	v_cmp_le_f32_e32 vcc, v2, v80
	s_waitcnt lgkmcnt(3)
	v_cmp_eq_f32_e64 s[0:1], v6, v18
	s_and_b64 s[0:1], s[0:1], s[16:17]
	v_cndmask_b32_e64 v20, 0, 1, vcc
	v_cmp_lt_f32_e32 vcc, v6, v18
	s_or_b64 s[0:1], vcc, s[0:1]
	v_cmp_le_f32_e32 vcc, v2, v18
	v_add_u32_e32 v15, v15, v16
	v_cndmask_b32_e64 v16, 0, 1, s[0:1]
	v_addc_co_u32_e32 v20, vcc, v19, v20, vcc
	v_cmp_lt_f32_e32 vcc, v1, v81
	v_cmp_eq_f32_e64 s[0:1], v2, v82
	s_and_b64 s[0:1], s[4:5], s[0:1]
	v_cndmask_b32_e64 v32, 0, 1, vcc
	v_cmp_lt_f32_e32 vcc, v0, v81
	v_readlane_b32 s16, v251, 56
	v_readlane_b32 s17, v251, 57
	v_cndmask_b32_e64 v24, 0, 1, vcc
	v_cmp_lt_f32_e32 vcc, v6, v81
	s_or_b64 s[24:25], vcc, s[24:25]
	v_cmp_le_f32_e32 vcc, v2, v81
	v_cndmask_b32_e64 v19, 0, 1, s[24:25]
	v_cmp_eq_u32_e64 s[24:25], s15, v46
	v_cndmask_b32_e64 v23, 0, 1, vcc
	v_cmp_le_f32_e32 vcc, v2, v21
	s_nop 1
	v_addc_co_u32_e32 v20, vcc, v20, v23, vcc
	v_cmp_lt_f32_e32 vcc, v1, v82
	s_nop 1
	v_cndmask_b32_e64 v34, 0, 1, vcc
	v_cmp_lt_f32_e32 vcc, v0, v82
	s_nop 1
	v_cndmask_b32_e64 v30, 0, 1, vcc
	v_cmp_lt_f32_e32 vcc, v6, v82
	s_nop 1
	v_cndmask_b32_e64 v23, 0, 1, vcc
	v_cmp_lt_f32_e32 vcc, v2, v82
	s_or_b64 s[0:1], vcc, s[0:1]
	v_cndmask_b32_e64 v25, 0, 1, s[0:1]
	v_cmp_eq_f32_e64 s[0:1], v2, v26
	v_cmp_lt_f32_e32 vcc, v2, v26
	s_and_b64 s[0:1], s[0:1], s[16:17]
	s_or_b64 s[0:1], vcc, s[0:1]
	v_cmp_lt_f32_e32 vcc, v1, v83
	v_add_u32_e32 v20, v20, v25
	v_cndmask_b32_e64 v25, 0, 1, s[0:1]
	v_cndmask_b32_e64 v36, 0, 1, vcc
	v_cmp_lt_f32_e32 vcc, v0, v83
	v_cmp_eq_f32_e64 s[0:1], v2, v83
	s_and_b64 s[0:1], s[8:9], s[0:1]
	v_cndmask_b32_e64 v35, 0, 1, vcc
	v_cmp_lt_f32_e32 vcc, v6, v83
	v_readlane_b32 s16, v251, 58
	v_readlane_b32 s17, v251, 59
	v_cndmask_b32_e64 v33, 0, 1, vcc
	v_cmp_lt_f32_e32 vcc, v2, v83
	s_or_b64 s[0:1], vcc, s[0:1]
	v_cmp_eq_u32_e32 vcc, s13, v46
	v_cndmask_b32_e64 v28, 0, 1, s[0:1]
	v_cmp_eq_u32_e64 s[0:1], s13, v47
	s_or_b64 vcc, vcc, s[24:25]
	v_cndmask_b32_e32 v27, v27, v161, vcc
	s_or_b64 vcc, s[0:1], s[26:27]
	v_cndmask_b32_e32 v31, v31, v161, vcc
	v_cmp_le_f32_e32 vcc, v31, v84
	ds_bpermute_b32 v72, v142, v31
	ds_bpermute_b32 v77, v143, v31
	v_cndmask_b32_e64 v68, 0, 1, vcc
	v_cmp_le_f32_e32 vcc, v31, v55
	ds_bpermute_b32 v88, v144, v31
	s_waitcnt lgkmcnt(2)
	v_cmp_eq_f32_e64 s[0:1], v31, v72
	v_addc_co_u32_e32 v68, vcc, 0, v68, vcc
	v_cmp_le_f32_e32 vcc, v27, v84
	s_and_b64 s[0:1], s[4:5], s[0:1]
	ds_bpermute_b32 v95, v145, v31
	v_cndmask_b32_e64 v69, 0, 1, vcc
	v_cmp_le_f32_e32 vcc, v27, v55
	ds_bpermute_b32 v89, v142, v27
	s_waitcnt lgkmcnt(2)
	v_cmp_eq_f32_e64 s[24:25], v31, v88
	v_addc_co_u32_e32 v69, vcc, 0, v69, vcc
	v_cmp_le_f32_e32 vcc, v31, v86
	s_and_b64 s[24:25], s[8:9], s[24:25]
	ds_bpermute_b32 v166, v143, v27
	v_cndmask_b32_e64 v70, 0, 1, vcc
	v_cmp_le_f32_e32 vcc, v27, v86
	ds_bpermute_b32 v168, v144, v27
	v_cmp_eq_u32_e64 s[26:27], s15, v49
	v_cndmask_b32_e64 v71, 0, 1, vcc
	v_cmp_le_f32_e32 vcc, v31, v9
	ds_bpermute_b32 v176, v145, v27
	s_nop 0
	v_addc_co_u32_e32 v68, vcc, v68, v70, vcc
	v_cmp_le_f32_e32 vcc, v27, v9
	s_nop 1
	v_addc_co_u32_e32 v69, vcc, v69, v71, vcc
	v_cmp_le_f32_e32 vcc, v31, v85
	s_nop 1
	v_cndmask_b32_e64 v70, 0, 1, vcc
	v_cmp_le_f32_e32 vcc, v27, v85
	s_nop 1
	v_cndmask_b32_e64 v71, 0, 1, vcc
	v_cmp_le_f32_e32 vcc, v31, v13
	s_nop 1
	v_addc_co_u32_e32 v68, vcc, v68, v70, vcc
	v_cmp_le_f32_e32 vcc, v27, v13
	s_nop 1
	v_addc_co_u32_e32 v69, vcc, v69, v71, vcc
	v_cmp_le_f32_e32 vcc, v31, v87
	s_nop 1
	v_cndmask_b32_e64 v70, 0, 1, vcc
	v_cmp_le_f32_e32 vcc, v27, v87
	s_nop 1
	v_cndmask_b32_e64 v71, 0, 1, vcc
	v_cmp_le_f32_e32 vcc, v31, v12
	s_nop 1
	v_addc_co_u32_e32 v68, vcc, v68, v70, vcc
	v_cmp_le_f32_e32 vcc, v27, v12
	s_nop 1
	v_addc_co_u32_e32 v69, vcc, v69, v71, vcc
	v_cmp_le_f32_e32 vcc, v31, v80
	s_nop 1
	v_cndmask_b32_e64 v70, 0, 1, vcc
	v_cmp_le_f32_e32 vcc, v27, v80
	s_nop 1
	v_cndmask_b32_e64 v71, 0, 1, vcc
	v_cmp_le_f32_e32 vcc, v31, v18
	s_nop 1
	v_addc_co_u32_e32 v68, vcc, v68, v70, vcc
	v_cmp_le_f32_e32 vcc, v27, v18
	s_nop 1
	v_addc_co_u32_e32 v69, vcc, v69, v71, vcc
	v_cmp_le_f32_e32 vcc, v31, v81
	s_nop 1
	v_cndmask_b32_e64 v70, 0, 1, vcc
	v_cmp_le_f32_e32 vcc, v27, v81
	s_nop 1
	v_cndmask_b32_e64 v71, 0, 1, vcc
	v_cmp_le_f32_e32 vcc, v31, v21
	s_nop 1
	v_addc_co_u32_e32 v68, vcc, v68, v70, vcc
	v_cmp_le_f32_e32 vcc, v27, v21
	s_nop 1
	v_addc_co_u32_e32 v69, vcc, v69, v71, vcc
	v_cmp_le_f32_e32 vcc, v31, v82
	s_nop 1
	v_cndmask_b32_e64 v70, 0, 1, vcc
	v_cmp_le_f32_e32 vcc, v27, v82
	s_nop 1
	v_cndmask_b32_e64 v71, 0, 1, vcc
	v_cmp_le_f32_e32 vcc, v31, v26
	s_nop 1
	v_addc_co_u32_e32 v68, vcc, v68, v70, vcc
	v_cmp_le_f32_e32 vcc, v27, v26
	s_nop 1
	v_addc_co_u32_e32 v69, vcc, v69, v71, vcc
	v_cmp_le_f32_e32 vcc, v31, v83
	s_nop 1
	v_cndmask_b32_e64 v70, 0, 1, vcc
	v_cmp_le_f32_e32 vcc, v27, v83
	s_nop 1
	v_cndmask_b32_e64 v71, 0, 1, vcc
	v_cmp_le_f32_e32 vcc, v31, v29
	s_nop 1
	v_addc_co_u32_e32 v68, vcc, v68, v70, vcc
	v_cmp_le_f32_e32 vcc, v27, v29
	s_nop 1
	v_addc_co_u32_e32 v69, vcc, v69, v71, vcc
	v_cmp_lt_f32_e32 vcc, v1, v72
	v_mov_b32_e32 v71, v64
	v_mov_b32_e32 v64, v67
	v_cndmask_b32_e64 v73, 0, 1, vcc
	v_cmp_lt_f32_e32 vcc, v0, v72
	v_mov_b32_e32 v67, v60
	v_mov_b32_e32 v60, v63
	v_cndmask_b32_e64 v74, 0, 1, vcc
	v_cmp_lt_f32_e32 vcc, v6, v72
	s_nop 1
	v_cndmask_b32_e64 v75, 0, 1, vcc
	v_cmp_lt_f32_e32 vcc, v2, v72
	s_nop 1
	v_cndmask_b32_e64 v76, 0, 1, vcc
	v_cmp_lt_f32_e32 vcc, v31, v72
	s_or_b64 s[0:1], vcc, s[0:1]
	v_cndmask_b32_e64 v70, 0, 1, s[0:1]
	v_cmp_le_f32_e32 vcc, v27, v72
	v_cmp_eq_f32_e64 s[0:1], v31, v77
	v_add_u32_e32 v78, v68, v70
	v_cndmask_b32_e64 v68, 0, 1, vcc
	v_cmp_lt_f32_e32 vcc, v31, v77
	s_and_b64 s[0:1], s[0:1], s[16:17]
	s_or_b64 s[0:1], vcc, s[0:1]
	v_cmp_le_f32_e32 vcc, v27, v77
	v_cndmask_b32_e64 v79, 0, 1, s[0:1]
	s_waitcnt lgkmcnt(3)
	v_cmp_eq_f32_e64 s[0:1], v27, v89
	v_addc_co_u32_e32 v68, vcc, v69, v68, vcc
	v_cmp_lt_f32_e32 vcc, v1, v88
	s_and_b64 s[0:1], s[4:5], s[0:1]
	v_readlane_b32 s16, v251, 60
	v_cndmask_b32_e64 v90, 0, 1, vcc
	v_cmp_lt_f32_e32 vcc, v0, v88
	v_readlane_b32 s17, v251, 61
	v_mov_b32_e32 v70, v66
	v_cndmask_b32_e64 v91, 0, 1, vcc
	v_cmp_lt_f32_e32 vcc, v6, v88
	v_mov_b32_e32 v66, v62
	s_nop 0
	v_cndmask_b32_e64 v93, 0, 1, vcc
	v_cmp_lt_f32_e32 vcc, v2, v88
	s_nop 1
	v_cndmask_b32_e64 v94, 0, 1, vcc
	v_cmp_lt_f32_e32 vcc, v31, v88
	s_or_b64 s[24:25], vcc, s[24:25]
	v_cmp_le_f32_e32 vcc, v27, v88
	v_cndmask_b32_e64 v96, 0, 1, s[24:25]
	v_cmp_eq_u32_e64 s[24:25], s15, v48
	v_cndmask_b32_e64 v69, 0, 1, vcc
	v_cmp_le_f32_e32 vcc, v27, v95
	s_nop 1
	v_addc_co_u32_e32 v68, vcc, v68, v69, vcc
	v_cmp_lt_f32_e32 vcc, v1, v89
	s_nop 1
	v_cndmask_b32_e64 v97, 0, 1, vcc
	v_cmp_lt_f32_e32 vcc, v0, v89
	s_nop 1
	v_cndmask_b32_e64 v162, 0, 1, vcc
	v_cmp_lt_f32_e32 vcc, v6, v89
	s_nop 1
	v_cndmask_b32_e64 v163, 0, 1, vcc
	v_cmp_lt_f32_e32 vcc, v2, v89
	s_nop 1
	v_cndmask_b32_e64 v164, 0, 1, vcc
	v_cmp_lt_f32_e32 vcc, v31, v89
	s_nop 1
	v_cndmask_b32_e64 v165, 0, 1, vcc
	v_cmp_lt_f32_e32 vcc, v27, v89
	s_or_b64 s[0:1], vcc, s[0:1]
	v_cndmask_b32_e64 v69, 0, 1, s[0:1]
	s_waitcnt lgkmcnt(2)
	v_cmp_eq_f32_e64 s[0:1], v27, v166
	v_cmp_lt_f32_e32 vcc, v27, v166
	s_and_b64 s[0:1], s[0:1], s[16:17]
	s_or_b64 s[0:1], vcc, s[0:1]
	s_waitcnt lgkmcnt(1)
	v_cmp_lt_f32_e32 vcc, v1, v168
	v_add_u32_e32 v167, v68, v69
	v_cndmask_b32_e64 v69, v59, v57, s[2:3]
	v_cndmask_b32_e64 v170, 0, 1, vcc
	v_cmp_lt_f32_e32 vcc, v0, v168
	v_cndmask_b32_e64 v68, v92, v59, s[2:3]
	v_pk_fma_f32 v[68:69], v[68:69], 0.5, v[70:71] op_sel_hi:[1,0,1]
	v_cndmask_b32_e64 v171, 0, 1, vcc
	v_cmp_lt_f32_e32 vcc, v6, v168
	v_pk_add_f32 v[64:65], v[64:65], v[68:69]
	v_cndmask_b32_e64 v169, 0, 1, s[0:1]
	v_cndmask_b32_e64 v172, 0, 1, vcc
	v_cmp_lt_f32_e32 vcc, v2, v168
	v_cmp_eq_f32_e64 s[0:1], v27, v168
	v_pk_add_f32 v[64:65], v[66:67], v[64:65]
	v_cndmask_b32_e64 v173, 0, 1, vcc
	v_cmp_lt_f32_e32 vcc, v31, v168
	s_and_b64 s[0:1], s[8:9], s[0:1]
	v_pk_fma_f32 v[60:61], v[60:61], 0.5, v[64:65] op_sel_hi:[1,0,1]
	v_cndmask_b32_e64 v174, 0, 1, vcc
	v_cmp_lt_f32_e32 vcc, v27, v168
	s_or_b64 s[0:1], vcc, s[0:1]
	v_cmp_eq_u32_e32 vcc, s13, v48
	v_cndmask_b32_e64 v57, -1.0, v61, s[28:29]
	v_cmp_ge_u32_e64 s[28:29], s13, v48
	v_cndmask_b32_e64 v175, 0, 1, s[0:1]
	v_cmp_eq_u32_e64 s[0:1], s13, v49
	v_cndmask_b32_e64 v59, -1.0, v60, s[28:29]
	s_or_b64 vcc, vcc, s[24:25]
	v_cndmask_b32_e32 v59, v59, v161, vcc
	s_or_b64 vcc, s[0:1], s[26:27]
	v_cndmask_b32_e32 v57, v57, v161, vcc
	v_cmp_le_f32_e32 vcc, v57, v84
	ds_bpermute_b32 v63, v142, v57
	ds_bpermute_b32 v68, v143, v57
	v_cndmask_b32_e64 v60, 0, 1, vcc
	v_cmp_le_f32_e32 vcc, v57, v55
	ds_bpermute_b32 v70, v144, v57
	s_waitcnt lgkmcnt(2)
	v_cmp_eq_f32_e64 s[0:1], v57, v63
	v_addc_co_u32_e32 v60, vcc, 0, v60, vcc
	v_cmp_le_f32_e32 vcc, v59, v84
	s_and_b64 s[0:1], s[4:5], s[0:1]
	ds_bpermute_b32 v84, v145, v57
	v_cndmask_b32_e64 v61, 0, 1, vcc
	v_cmp_le_f32_e32 vcc, v59, v55
	s_waitcnt lgkmcnt(1)
	v_cmp_eq_f32_e64 s[24:25], v57, v70
	s_and_b64 s[24:25], s[8:9], s[24:25]
	v_addc_co_u32_e32 v55, vcc, 0, v61, vcc
	v_cmp_le_f32_e32 vcc, v57, v86
	ds_bpermute_b32 v186, v145, v59
	s_nop 0
	v_cndmask_b32_e64 v61, 0, 1, vcc
	v_cmp_le_f32_e32 vcc, v59, v86
	s_nop 1
	v_cndmask_b32_e64 v62, 0, 1, vcc
	v_cmp_le_f32_e32 vcc, v57, v9
	s_nop 1
	v_addc_co_u32_e32 v60, vcc, v60, v61, vcc
	v_cmp_le_f32_e32 vcc, v59, v9
	s_nop 1
	v_addc_co_u32_e32 v55, vcc, v55, v62, vcc
	v_cmp_le_f32_e32 vcc, v57, v85
	s_nop 1
	v_cndmask_b32_e64 v61, 0, 1, vcc
	v_cmp_le_f32_e32 vcc, v59, v85
	s_nop 1
	v_cndmask_b32_e64 v62, 0, 1, vcc
	v_cmp_le_f32_e32 vcc, v57, v13
	s_nop 1
	v_addc_co_u32_e32 v60, vcc, v60, v61, vcc
	v_cmp_le_f32_e32 vcc, v59, v13
	s_nop 1
	v_addc_co_u32_e32 v55, vcc, v55, v62, vcc
	v_cmp_le_f32_e32 vcc, v57, v87
	s_nop 1
	v_cndmask_b32_e64 v61, 0, 1, vcc
	v_cmp_le_f32_e32 vcc, v59, v87
	s_nop 1
	v_cndmask_b32_e64 v62, 0, 1, vcc
	v_cmp_le_f32_e32 vcc, v57, v12
	s_nop 1
	v_addc_co_u32_e32 v60, vcc, v60, v61, vcc
	v_cmp_le_f32_e32 vcc, v59, v12
	s_nop 1
	v_addc_co_u32_e32 v55, vcc, v55, v62, vcc
	v_cmp_le_f32_e32 vcc, v57, v80
	s_nop 1
	v_cndmask_b32_e64 v61, 0, 1, vcc
	v_cmp_le_f32_e32 vcc, v59, v80
	s_nop 1
	v_cndmask_b32_e64 v62, 0, 1, vcc
	v_cmp_le_f32_e32 vcc, v57, v18
	s_nop 1
	v_addc_co_u32_e32 v60, vcc, v60, v61, vcc
	v_cmp_le_f32_e32 vcc, v59, v18
	s_nop 1
	v_addc_co_u32_e32 v55, vcc, v55, v62, vcc
	v_cmp_le_f32_e32 vcc, v57, v81
	s_nop 1
	v_cndmask_b32_e64 v61, 0, 1, vcc
	v_cmp_le_f32_e32 vcc, v59, v81
	s_nop 1
	v_cndmask_b32_e64 v62, 0, 1, vcc
	v_cmp_le_f32_e32 vcc, v57, v21
	s_nop 1
	v_addc_co_u32_e32 v60, vcc, v60, v61, vcc
	v_cmp_le_f32_e32 vcc, v59, v21
	s_nop 1
	v_addc_co_u32_e32 v55, vcc, v55, v62, vcc
	v_cmp_le_f32_e32 vcc, v57, v82
	s_nop 1
	v_cndmask_b32_e64 v61, 0, 1, vcc
	v_cmp_le_f32_e32 vcc, v59, v82
	s_nop 1
	v_cndmask_b32_e64 v62, 0, 1, vcc
	v_cmp_le_f32_e32 vcc, v57, v26
	s_nop 1
	v_addc_co_u32_e32 v60, vcc, v60, v61, vcc
	v_cmp_le_f32_e32 vcc, v59, v26
	s_nop 1
	v_addc_co_u32_e32 v55, vcc, v55, v62, vcc
	v_cmp_le_f32_e32 vcc, v57, v83
	s_nop 1
	v_cndmask_b32_e64 v61, 0, 1, vcc
	v_cmp_le_f32_e32 vcc, v59, v83
	s_nop 1
	v_cndmask_b32_e64 v62, 0, 1, vcc
	v_cmp_le_f32_e32 vcc, v57, v29
	s_nop 1
	v_addc_co_u32_e32 v60, vcc, v60, v61, vcc
	v_cmp_le_f32_e32 vcc, v59, v29
	s_nop 1
	v_addc_co_u32_e32 v55, vcc, v55, v62, vcc
	v_cmp_le_f32_e32 vcc, v57, v72
	s_nop 1
	v_cndmask_b32_e64 v61, 0, 1, vcc
	v_cmp_le_f32_e32 vcc, v59, v72
	s_nop 1
	v_cndmask_b32_e64 v62, 0, 1, vcc
	v_cmp_le_f32_e32 vcc, v57, v77
	s_nop 1
	v_addc_co_u32_e32 v60, vcc, v60, v61, vcc
	v_cmp_le_f32_e32 vcc, v59, v77
	s_nop 1
	v_addc_co_u32_e32 v55, vcc, v55, v62, vcc
	v_cmp_le_f32_e32 vcc, v57, v88
	s_nop 1
	v_cndmask_b32_e64 v61, 0, 1, vcc
	v_cmp_le_f32_e32 vcc, v59, v88
	s_nop 1
	v_cndmask_b32_e64 v62, 0, 1, vcc
	v_cmp_le_f32_e32 vcc, v57, v95
	s_nop 1
	v_addc_co_u32_e32 v60, vcc, v60, v61, vcc
	v_cmp_le_f32_e32 vcc, v59, v95
	s_nop 1
	v_addc_co_u32_e32 v55, vcc, v55, v62, vcc
	v_cmp_le_f32_e32 vcc, v57, v89
	s_nop 1
	v_cndmask_b32_e64 v61, 0, 1, vcc
	v_cmp_le_f32_e32 vcc, v59, v89
	s_nop 1
	v_cndmask_b32_e64 v62, 0, 1, vcc
	v_cmp_le_f32_e32 vcc, v57, v166
	s_nop 1
	v_addc_co_u32_e32 v60, vcc, v60, v61, vcc
	v_cmp_le_f32_e32 vcc, v59, v166
	s_nop 1
	v_addc_co_u32_e32 v55, vcc, v55, v62, vcc
	v_cmp_le_f32_e32 vcc, v57, v168
	s_nop 1
	v_cndmask_b32_e64 v61, 0, 1, vcc
	v_cmp_le_f32_e32 vcc, v59, v168
	s_nop 1
	v_cndmask_b32_e64 v62, 0, 1, vcc
	v_cmp_le_f32_e32 vcc, v57, v176
	s_nop 1
	v_addc_co_u32_e32 v60, vcc, v60, v61, vcc
	v_cmp_le_f32_e32 vcc, v59, v176
	s_nop 1
	v_addc_co_u32_e32 v55, vcc, v55, v62, vcc
	v_cmp_lt_f32_e32 vcc, v1, v63
	s_nop 1
	v_cndmask_b32_e64 v61, 0, 1, vcc
	v_cmp_lt_f32_e32 vcc, v0, v63
	s_nop 1
	v_cndmask_b32_e64 v62, 0, 1, vcc
	v_cmp_lt_f32_e32 vcc, v6, v63
	s_nop 1
	v_cndmask_b32_e64 v64, 0, 1, vcc
	v_cmp_lt_f32_e32 vcc, v2, v63
	s_nop 1
	v_cndmask_b32_e64 v65, 0, 1, vcc
	v_cmp_lt_f32_e32 vcc, v31, v63
	s_nop 1
	v_cndmask_b32_e64 v66, 0, 1, vcc
	v_cmp_lt_f32_e32 vcc, v27, v63
	s_nop 1
	v_cndmask_b32_e64 v67, 0, 1, vcc
	v_cmp_lt_f32_e32 vcc, v57, v63
	s_or_b64 s[0:1], vcc, s[0:1]
	v_cndmask_b32_e64 v69, 0, 1, s[0:1]
	v_cmp_le_f32_e32 vcc, v59, v63
	v_cmp_eq_f32_e64 s[0:1], v57, v68
	s_and_b64 s[0:1], s[0:1], s[20:21]
	v_cndmask_b32_e64 v63, 0, 1, vcc
	v_cmp_lt_f32_e32 vcc, v57, v68
	s_or_b64 s[0:1], vcc, s[0:1]
	v_cmp_le_f32_e32 vcc, v59, v68
	v_add_u32_e32 v60, v60, v69
	v_cndmask_b32_e64 v69, 0, 1, s[0:1]
	v_addc_co_u32_e32 v55, vcc, v55, v63, vcc
	v_cmp_lt_f32_e32 vcc, v1, v70
	ds_bpermute_b32 v63, v142, v59
	s_waitcnt lgkmcnt(0)
	v_cmp_eq_f32_e64 s[0:1], v59, v63
	v_cndmask_b32_e64 v71, 0, 1, vcc
	v_cmp_lt_f32_e32 vcc, v0, v70
	s_and_b64 s[0:1], s[4:5], s[0:1]
	s_nop 0
	v_cndmask_b32_e64 v72, 0, 1, vcc
	v_cmp_lt_f32_e32 vcc, v6, v70
	s_nop 1
	v_cndmask_b32_e64 v80, 0, 1, vcc
	v_cmp_lt_f32_e32 vcc, v2, v70
	s_nop 1
	v_cndmask_b32_e64 v81, 0, 1, vcc
	v_cmp_lt_f32_e32 vcc, v31, v70
	s_nop 1
	v_cndmask_b32_e64 v82, 0, 1, vcc
	v_cmp_lt_f32_e32 vcc, v27, v70
	s_nop 1
	v_cndmask_b32_e64 v83, 0, 1, vcc
	v_cmp_lt_f32_e32 vcc, v57, v70
	s_or_b64 s[24:25], vcc, s[24:25]
	v_cmp_le_f32_e32 vcc, v59, v70
	v_cndmask_b32_e64 v85, 0, 1, s[24:25]
	s_nop 0
	v_cndmask_b32_e64 v70, 0, 1, vcc
	v_cmp_le_f32_e32 vcc, v59, v84
	s_nop 1
	v_addc_co_u32_e32 v55, vcc, v55, v70, vcc
	v_cmp_lt_f32_e32 vcc, v1, v63
	s_nop 1
	v_cndmask_b32_e64 v70, 0, 1, vcc
	v_cmp_lt_f32_e32 vcc, v0, v63
	s_nop 1
	v_cndmask_b32_e64 v86, 0, 1, vcc
	v_cmp_lt_f32_e32 vcc, v6, v63
	s_nop 1
	v_cndmask_b32_e64 v87, 0, 1, vcc
	v_cmp_lt_f32_e32 vcc, v2, v63
	s_nop 1
	v_cndmask_b32_e64 v88, 0, 1, vcc
	v_cmp_lt_f32_e32 vcc, v31, v63
	s_nop 1
	v_cndmask_b32_e64 v89, 0, 1, vcc
	v_cmp_lt_f32_e32 vcc, v27, v63
	s_nop 1
	v_cndmask_b32_e64 v92, 0, 1, vcc
	v_cmp_lt_f32_e32 vcc, v57, v63
	s_nop 1
	v_cndmask_b32_e64 v168, 0, 1, vcc
	v_cmp_lt_f32_e32 vcc, v59, v63
	ds_bpermute_b32 v63, v143, v59
	s_or_b64 s[0:1], vcc, s[0:1]
	v_cndmask_b32_e64 v177, 0, 1, s[0:1]
	v_add_u32_e32 v55, v55, v177
	ds_bpermute_b32 v177, v144, v59
	s_waitcnt lgkmcnt(1)
	v_cmp_eq_f32_e64 s[0:1], v59, v63
	v_cmp_lt_f32_e32 vcc, v59, v63
	s_and_b64 s[0:1], s[0:1], s[22:23]
	s_or_b64 s[0:1], vcc, s[0:1]
	s_waitcnt lgkmcnt(0)
	v_cmp_lt_f32_e32 vcc, v1, v177
	v_cndmask_b32_e64 v178, 0, 1, s[0:1]
	v_cmp_eq_f32_e64 s[0:1], v59, v177
	v_cndmask_b32_e64 v179, 0, 1, vcc
	v_cmp_lt_f32_e32 vcc, v0, v177
	s_and_b64 s[0:1], s[8:9], s[0:1]
	s_nop 0
	v_cndmask_b32_e64 v180, 0, 1, vcc
	v_cmp_lt_f32_e32 vcc, v6, v177
	s_nop 1
	v_cndmask_b32_e64 v181, 0, 1, vcc
	v_cmp_lt_f32_e32 vcc, v2, v177
	s_nop 1
	v_cndmask_b32_e64 v182, 0, 1, vcc
	v_cmp_lt_f32_e32 vcc, v31, v177
	s_nop 1
	v_cndmask_b32_e64 v183, 0, 1, vcc
	v_cmp_lt_f32_e32 vcc, v27, v177
	s_nop 1
	v_cndmask_b32_e64 v184, 0, 1, vcc
	v_cmp_lt_f32_e32 vcc, v57, v177
	s_nop 1
	v_cndmask_b32_e64 v185, 0, 1, vcc
	v_cmp_lt_f32_e32 vcc, v59, v177
	s_or_b64 s[0:1], vcc, s[0:1]
	v_cmp_lt_f32_e32 vcc, v1, v9
	v_cndmask_b32_e64 v177, 0, 1, s[0:1]
	s_nop 0
	v_addc_co_u32_e32 v3, vcc, v4, v3, vcc
	v_add_u32_e32 v3, v3, v8
	v_cmp_lt_f32_e32 vcc, v1, v13
	s_nop 1
	v_addc_co_u32_e32 v3, vcc, v3, v10, vcc
	v_cmp_lt_f32_e32 vcc, v1, v12
	s_nop 1
	v_addc_co_u32_e32 v3, vcc, v3, v14, vcc
	v_cmp_lt_f32_e32 vcc, v1, v18
	s_nop 1
	v_addc_co_u32_e32 v3, vcc, v3, v22, vcc
	v_cmp_lt_f32_e32 vcc, v1, v21
	s_nop 1
	v_addc_co_u32_e32 v3, vcc, v3, v32, vcc
	v_cmp_lt_f32_e32 vcc, v1, v26
	s_nop 1
	v_addc_co_u32_e32 v3, vcc, v3, v34, vcc
	v_cmp_lt_f32_e32 vcc, v1, v29
	s_nop 1
	v_addc_co_u32_e32 v3, vcc, v3, v36, vcc
	v_cmp_lt_f32_e32 vcc, v1, v77
	s_nop 1
	v_addc_co_u32_e32 v3, vcc, v3, v73, vcc
	v_cmp_lt_f32_e32 vcc, v1, v95
	s_nop 1
	v_addc_co_u32_e32 v3, vcc, v3, v90, vcc
	v_cmp_lt_f32_e32 vcc, v1, v166
	s_nop 1
	v_addc_co_u32_e32 v3, vcc, v3, v97, vcc
	v_cmp_lt_f32_e32 vcc, v1, v176
	s_nop 1
	v_addc_co_u32_e32 v3, vcc, v3, v170, vcc
	v_cmp_lt_f32_e32 vcc, v1, v68
	s_nop 1
	v_addc_co_u32_e32 v3, vcc, v3, v61, vcc
	v_cmp_lt_f32_e32 vcc, v1, v84
	s_nop 1
	v_addc_co_u32_e32 v3, vcc, v3, v71, vcc
	v_cmp_lt_f32_e32 vcc, v1, v63
	s_nop 1
	v_addc_co_u32_e32 v3, vcc, v3, v70, vcc
	v_cmp_lt_f32_e32 vcc, v1, v186
	s_nop 1
	v_addc_co_u32_e32 v1, vcc, v3, v179, vcc
	v_cmp_lt_f32_e32 vcc, v0, v12
	s_nop 1
	v_addc_co_u32_e32 v3, vcc, v5, v7, vcc
	v_add_u32_e32 v3, v3, v11
	v_cmp_lt_f32_e32 vcc, v0, v18
	s_nop 1
	v_addc_co_u32_e32 v3, vcc, v3, v17, vcc
	v_cmp_lt_f32_e32 vcc, v0, v21
	s_nop 1
	v_addc_co_u32_e32 v3, vcc, v3, v24, vcc
	v_cmp_lt_f32_e32 vcc, v0, v26
	s_nop 1
	v_addc_co_u32_e32 v3, vcc, v3, v30, vcc
	v_cmp_lt_f32_e32 vcc, v0, v29
	s_nop 1
	v_addc_co_u32_e32 v3, vcc, v3, v35, vcc
	v_cmp_lt_f32_e32 vcc, v0, v77
	s_nop 1
	v_addc_co_u32_e32 v3, vcc, v3, v74, vcc
	v_cmp_lt_f32_e32 vcc, v0, v95
	s_nop 1
	v_addc_co_u32_e32 v3, vcc, v3, v91, vcc
	v_cmp_lt_f32_e32 vcc, v0, v166
	s_nop 1
	v_addc_co_u32_e32 v3, vcc, v3, v162, vcc
	v_cmp_lt_f32_e32 vcc, v0, v176
	s_nop 1
	v_addc_co_u32_e32 v3, vcc, v3, v171, vcc
	v_cmp_lt_f32_e32 vcc, v0, v68
	s_nop 1
	v_addc_co_u32_e32 v3, vcc, v3, v62, vcc
	v_cmp_lt_f32_e32 vcc, v0, v84
	s_nop 1
	v_addc_co_u32_e32 v3, vcc, v3, v72, vcc
	v_cmp_lt_f32_e32 vcc, v0, v63
	s_nop 1
	v_addc_co_u32_e32 v3, vcc, v3, v86, vcc
	v_cmp_lt_f32_e32 vcc, v0, v186
	s_nop 1
	v_addc_co_u32_e32 v0, vcc, v3, v180, vcc
	v_cmp_lt_f32_e32 vcc, v6, v21
	s_nop 1
	v_addc_co_u32_e32 v3, vcc, v15, v16, vcc
	v_add_u32_e32 v3, v3, v19
	v_cmp_lt_f32_e32 vcc, v6, v26
	s_nop 1
	v_addc_co_u32_e32 v3, vcc, v3, v23, vcc
	v_cmp_lt_f32_e32 vcc, v6, v29
	s_nop 1
	v_addc_co_u32_e32 v3, vcc, v3, v33, vcc
	v_cmp_lt_f32_e32 vcc, v6, v77
	s_nop 1
	v_addc_co_u32_e32 v3, vcc, v3, v75, vcc
	v_cmp_lt_f32_e32 vcc, v6, v95
	s_nop 1
	v_addc_co_u32_e32 v3, vcc, v3, v93, vcc
	v_cmp_lt_f32_e32 vcc, v6, v166
	s_nop 1
	v_addc_co_u32_e32 v3, vcc, v3, v163, vcc
	v_cmp_lt_f32_e32 vcc, v6, v176
	s_nop 1
	v_addc_co_u32_e32 v3, vcc, v3, v172, vcc
	v_cmp_lt_f32_e32 vcc, v6, v68
	s_nop 1
	v_addc_co_u32_e32 v3, vcc, v3, v64, vcc
	v_cmp_lt_f32_e32 vcc, v6, v84
	s_nop 1
	v_addc_co_u32_e32 v3, vcc, v3, v80, vcc
	v_cmp_lt_f32_e32 vcc, v6, v63
	s_nop 1
	v_addc_co_u32_e32 v3, vcc, v3, v87, vcc
	v_cmp_lt_f32_e32 vcc, v6, v186
	s_nop 1
	v_addc_co_u32_e32 v3, vcc, v3, v181, vcc
	v_cmp_lt_f32_e32 vcc, v2, v29
	s_nop 1
	v_addc_co_u32_e32 v4, vcc, v20, v25, vcc
	v_add_u32_e32 v4, v4, v28
	v_cmp_lt_f32_e32 vcc, v2, v77
	s_nop 1
	v_addc_co_u32_e32 v4, vcc, v4, v76, vcc
	v_cmp_lt_f32_e32 vcc, v2, v95
	s_nop 1
	v_addc_co_u32_e32 v4, vcc, v4, v94, vcc
	v_cmp_lt_f32_e32 vcc, v2, v166
	s_nop 1
	v_addc_co_u32_e32 v4, vcc, v4, v164, vcc
	v_cmp_lt_f32_e32 vcc, v2, v176
	s_nop 1
	v_addc_co_u32_e32 v4, vcc, v4, v173, vcc
	v_cmp_lt_f32_e32 vcc, v2, v68
	s_nop 1
	v_addc_co_u32_e32 v4, vcc, v4, v65, vcc
	v_cmp_lt_f32_e32 vcc, v2, v84
	s_nop 1
	v_addc_co_u32_e32 v4, vcc, v4, v81, vcc
	v_cmp_lt_f32_e32 vcc, v2, v63
	s_nop 1
	v_addc_co_u32_e32 v4, vcc, v4, v88, vcc
	v_cmp_lt_f32_e32 vcc, v2, v186
	s_nop 1
	v_addc_co_u32_e32 v2, vcc, v4, v182, vcc
	v_cmp_lt_f32_e32 vcc, v31, v95
	s_nop 1
	v_addc_co_u32_e32 v4, vcc, v78, v79, vcc
	v_add_u32_e32 v4, v4, v96
	v_cmp_lt_f32_e32 vcc, v31, v166
	s_nop 1
	v_addc_co_u32_e32 v4, vcc, v4, v165, vcc
	v_cmp_lt_f32_e32 vcc, v31, v176
	s_nop 1
	v_addc_co_u32_e32 v4, vcc, v4, v174, vcc
	v_cmp_lt_f32_e32 vcc, v31, v68
	s_nop 1
	v_addc_co_u32_e32 v4, vcc, v4, v66, vcc
	v_cmp_lt_f32_e32 vcc, v31, v84
	s_nop 1
	v_addc_co_u32_e32 v4, vcc, v4, v82, vcc
	v_cmp_lt_f32_e32 vcc, v31, v63
	s_nop 1
	v_addc_co_u32_e32 v4, vcc, v4, v89, vcc
	v_cmp_lt_f32_e32 vcc, v31, v186
	s_nop 1
	v_addc_co_u32_e32 v4, vcc, v4, v183, vcc
	v_cmp_lt_f32_e32 vcc, v27, v176
	s_nop 1
	v_addc_co_u32_e32 v5, vcc, v167, v169, vcc
	v_add_u32_e32 v5, v5, v175
	v_cmp_lt_f32_e32 vcc, v27, v68
	s_nop 1
	v_addc_co_u32_e32 v5, vcc, v5, v67, vcc
	v_cmp_lt_f32_e32 vcc, v27, v84
	s_nop 1
	v_addc_co_u32_e32 v5, vcc, v5, v83, vcc
	v_cmp_lt_f32_e32 vcc, v27, v63
	s_nop 1
	v_addc_co_u32_e32 v5, vcc, v5, v92, vcc
	v_cmp_lt_f32_e32 vcc, v27, v186
	s_nop 1
	v_addc_co_u32_e32 v5, vcc, v5, v184, vcc
	v_cmp_lt_f32_e32 vcc, v57, v84
	s_nop 1
	v_addc_co_u32_e32 v6, vcc, v60, v69, vcc
	v_add_u32_e32 v6, v6, v85
	v_cmp_lt_f32_e32 vcc, v57, v63
	s_nop 1
	v_addc_co_u32_e32 v6, vcc, v6, v168, vcc
	v_cmp_lt_f32_e32 vcc, v57, v186
	s_nop 1
	v_addc_co_u32_e32 v6, vcc, v6, v185, vcc
	v_cmp_lt_f32_e32 vcc, v59, v186
	s_nop 1
	v_addc_co_u32_e32 v7, vcc, v55, v178, vcc
	v_cmp_gt_u32_e32 vcc, 8, v1
	v_add_u32_e32 v7, v7, v177
	s_nop 0
	v_cndmask_b32_e32 v1, 0, v132, vcc
	v_cmp_gt_u32_e32 vcc, 8, v0
	s_nop 1
	v_cndmask_b32_e32 v0, 0, v133, vcc
	v_cmp_gt_u32_e32 vcc, 8, v3
	v_or_b32_e32 v0, v0, v1
	s_nop 0
	v_cndmask_b32_e32 v1, 0, v134, vcc
	v_cmp_gt_u32_e32 vcc, 8, v2
	s_nop 1
	v_cndmask_b32_e32 v2, 0, v135, vcc
	v_cmp_gt_u32_e32 vcc, 8, v4
	v_or3_b32 v0, v0, v1, v2
	s_nop 0
	v_cndmask_b32_e32 v1, 0, v136, vcc
	v_cmp_gt_u32_e32 vcc, 8, v5
	s_nop 1
	v_cndmask_b32_e32 v2, 0, v137, vcc
	v_cmp_gt_u32_e32 vcc, 8, v6
	v_or3_b32 v0, v0, v1, v2
	s_nop 0
	v_cndmask_b32_e32 v1, 0, v138, vcc
	v_cmp_gt_u32_e32 vcc, 8, v7
	s_nop 1
	v_cndmask_b32_e32 v2, 0, v139, vcc
	v_or3_b32 v0, v0, v1, v2
	ds_bpermute_b32 v1, v146, v0
	s_waitcnt lgkmcnt(0)
	v_or_b32_e32 v0, v0, v1
	ds_bpermute_b32 v1, v147, v0
	s_and_saveexec_b64 s[0:1], s[2:3]
	s_cbranch_execz .LBB0_2006
	s_bfe_u32 s13, s14, 0x10007
	s_lshl_b32 s12, s12, 1
	s_or_b32 s12, s12, s13
	s_ashr_i32 s13, s12, 31
	s_lshl_b64 s[12:13], s[12:13], 13
	v_readlane_b32 s14, v251, 50
	s_add_u32 s12, s14, s12
	v_readlane_b32 s14, v251, 51
	s_waitcnt lgkmcnt(0)
	v_or_b32_e32 v0, v0, v1
	s_addc_u32 s13, s14, s13
	v_lshlrev_b32_e32 v1, 2, v53
	global_store_dword v1, v0, s[12:13]
	s_branch .LBB0_2006
